# RWKV phase: the S5 parameter blocks of a chain are fetched with wide loads before the serial setup gathers (cache warming)
# baseline (speedup 1.0000x reference)
.LBB0_264:
.LBB0_265:
	s_lshl_b32 s2, s56, 2
	s_load_dwordx2 s[8:9], s[0:1], 0xa0
	s_load_dwordx4 s[68:71], s[0:1], 0x90
	s_and_b32 s2, s2, 28
	s_or_b32 s2, s2, s96
	s_load_dwordx4 s[28:31], s[0:1], 0xa8
	v_lshlrev_b32_e32 v176, 4, v98
	s_lshl_b32 s3, s2, 12
	v_add_u32_e32 v176, s3, v176
	s_waitcnt lgkmcnt(0)
	global_load_dwordx4 v[180:183], v176, s[28:29]
	global_load_dwordx4 v[180:183], v176, s[28:29] offset:1024
	global_load_dwordx4 v[180:183], v176, s[28:29] offset:2048
	global_load_dwordx4 v[180:183], v176, s[28:29] offset:3072
	global_load_dwordx4 v[180:183], v176, s[30:31]
	global_load_dwordx4 v[180:183], v176, s[30:31] offset:1024
	global_load_dwordx4 v[180:183], v176, s[30:31] offset:2048
	global_load_dwordx4 v[180:183], v176, s[30:31] offset:3072
	s_load_dwordx4 s[28:31], s[0:1], 0xb8
	s_waitcnt lgkmcnt(0)
	global_load_dwordx4 v[184:187], v176, s[28:29]
	global_load_dwordx4 v[184:187], v176, s[28:29] offset:1024
	global_load_dwordx4 v[184:187], v176, s[28:29] offset:2048
	global_load_dwordx4 v[184:187], v176, s[28:29] offset:3072
	global_load_dwordx4 v[184:187], v176, s[30:31]
	global_load_dwordx4 v[184:187], v176, s[30:31] offset:1024
	global_load_dwordx4 v[184:187], v176, s[30:31] offset:2048
	global_load_dwordx4 v[184:187], v176, s[30:31] offset:3072
	s_lshl_b32 s3, s2, 2
	v_mov_b32_e32 v1, s3
	s_waitcnt lgkmcnt(0)
	global_load_dword v1, v1, s[8:9]
	s_lshl_b32 s3, s2, 6
	v_or_b32_e32 v2, s3, v98
	v_lshlrev_b32_e32 v2, 2, v2
	global_load_dword v3, v2, s[70:71]
	global_load_dword v25, v2, s[68:69]
	s_mov_b32 s8, 0x3fb8aa3b
	s_waitcnt vmcnt(0)
	v_mul_f32_e32 v2, 0x3fb8aa3b, v1
	v_fma_f32 v4, v1, s8, -v2
	v_rndne_f32_e32 v5, v2
	v_fmac_f32_e32 v4, 0x32a5705f, v1
	v_sub_f32_e32 v2, v2, v5
	v_add_f32_e32 v2, v2, v4
	v_cvt_i32_f32_e32 v5, v5
	v_exp_f32_e32 v2, v2
	v_cmp_ngt_f32_e32 vcc, s58, v1
	s_brev_b32 s8, 18
	v_ldexp_f32 v2, v2, v5
	v_cndmask_b32_e32 v2, 0, v2, vcc
	v_cmp_nlt_f32_e32 vcc, s59, v1
	s_nop 1
	v_cndmask_b32_e32 v57, v241, v2, vcc
	v_mul_f32_e32 v13, v57, v3
	v_and_b32_e32 v56, 0x7fffffff, v13
	v_lshrrev_b32_e32 v1, 23, v56
	v_and_b32_e32 v3, 0x7fffff, v56
	v_cmp_nlt_f32_e64 s[28:29], |v13|, s8
	v_add_u32_e32 v2, 0xffffff88, v1
	v_or_b32_e32 v1, 0x800000, v3
	s_and_saveexec_b64 s[8:9], s[28:29]
	s_xor_b64 s[30:31], exec, s[8:9]
	s_cbranch_execz .LBB0_267
	v_cmp_lt_u32_e32 vcc, 63, v2
	s_mov_b32 s8, 0xfe5163ab
	v_mov_b32_e32 v7, v0
	v_cndmask_b32_e32 v3, 0, v236, vcc
	v_add_u32_e32 v3, v3, v2
	v_cmp_lt_u32_e64 s[50:51], 31, v3
	v_mov_b32_e32 v9, v0
	v_mov_b32_e32 v11, v0
	v_cndmask_b32_e64 v4, 0, v237, s[50:51]
	v_add_u32_e32 v3, v4, v3
	v_cmp_lt_u32_e64 s[52:53], 31, v3
	v_mov_b32_e32 v15, v0
	v_mov_b32_e32 v17, v0
	v_cndmask_b32_e64 v4, 0, v237, s[52:53]
	v_add_u32_e32 v3, v4, v3
	v_mad_u64_u32 v[4:5], s[8:9], v1, s8, 0
	v_mov_b32_e32 v6, v5
	s_mov_b32 s8, 0x3c439041
	v_mad_u64_u32 v[6:7], s[8:9], v1, s8, v[6:7]
	v_mov_b32_e32 v8, v7
	s_mov_b32 s8, 0xdb629599
	v_mad_u64_u32 v[8:9], s[8:9], v1, s8, v[8:9]
	v_mov_b32_e32 v10, v9
	s_mov_b32 s8, 0xf534ddc0
	v_mad_u64_u32 v[10:11], s[8:9], v1, s8, v[10:11]
	v_mov_b32_e32 v14, v11
	s_mov_b32 s8, 0xfc2757d1
	v_mad_u64_u32 v[14:15], s[8:9], v1, s8, v[14:15]
	v_mov_b32_e32 v16, v15
	s_mov_b32 s8, 0x4e441529
	v_mad_u64_u32 v[16:17], s[8:9], v1, s8, v[16:17]
	v_mov_b32_e32 v26, v17
	v_mov_b32_e32 v27, v0
	s_mov_b32 s8, 0xa2f9836e
	v_mad_u64_u32 v[26:27], s[8:9], v1, s8, v[26:27]
	v_cndmask_b32_e32 v5, v16, v10, vcc
	v_cndmask_b32_e32 v7, v26, v14, vcc
	v_cndmask_b32_e32 v11, v27, v16, vcc
	v_cndmask_b32_e64 v9, v7, v5, s[50:51]
	v_cndmask_b32_e64 v7, v11, v7, s[50:51]
	v_cndmask_b32_e32 v11, v14, v8, vcc
	v_cndmask_b32_e64 v5, v5, v11, s[50:51]
	v_cndmask_b32_e64 v7, v7, v9, s[52:53]
	v_cndmask_b32_e64 v9, v9, v5, s[52:53]
	v_sub_u32_e32 v12, 32, v3
	v_alignbit_b32 v14, v7, v9, v12
	v_cmp_eq_u32_e64 s[54:55], 0, v3
	v_cndmask_b32_e32 v6, v10, v6, vcc
	v_cndmask_b32_e32 v4, v8, v4, vcc
	v_cndmask_b32_e64 v3, v14, v7, s[54:55]
	v_cndmask_b32_e64 v7, v11, v6, s[50:51]
	v_cndmask_b32_e64 v5, v5, v7, s[52:53]
	v_alignbit_b32 v10, v9, v5, v12
	v_cndmask_b32_e64 v9, v10, v9, s[54:55]
	v_bfe_u32 v14, v3, 29, 1
	v_cndmask_b32_e64 v4, v6, v4, s[50:51]
	v_alignbit_b32 v10, v3, v9, 30
	v_sub_u32_e32 v15, 0, v14
	v_cndmask_b32_e64 v4, v7, v4, s[52:53]
	v_xor_b32_e32 v10, v10, v15
	v_alignbit_b32 v6, v5, v4, v12
	v_cndmask_b32_e64 v5, v6, v5, s[54:55]
	v_ffbh_u32_e32 v7, v10
	v_alignbit_b32 v6, v9, v5, 30
	v_min_u32_e32 v7, 32, v7
	v_alignbit_b32 v4, v5, v4, 30
	v_xor_b32_e32 v6, v6, v15
	v_sub_u32_e32 v8, 31, v7
	v_xor_b32_e32 v4, v4, v15
	v_alignbit_b32 v9, v10, v6, v8
	v_alignbit_b32 v4, v6, v4, v8
	v_alignbit_b32 v5, v9, v4, 9
	v_ffbh_u32_e32 v6, v5
	v_min_u32_e32 v6, 32, v6
	v_lshrrev_b32_e32 v11, 29, v3
	v_not_b32_e32 v8, v6
	v_alignbit_b32 v4, v5, v4, v8
	v_lshlrev_b32_e32 v5, 31, v11
	v_or_b32_e32 v8, 0x33000000, v5
	v_add_lshl_u32 v6, v6, v7, 23
	v_lshrrev_b32_e32 v4, 9, v4
	v_sub_u32_e32 v6, v8, v6
	v_or_b32_e32 v5, 0.5, v5
	v_lshlrev_b32_e32 v7, 23, v7
	v_or_b32_e32 v4, v6, v4
	v_lshrrev_b32_e32 v6, 9, v9
	v_sub_u32_e32 v5, v5, v7
	v_or_b32_e32 v5, v6, v5
	v_mul_f32_e32 v6, 0x3fc90fda, v5
	s_mov_b32 s8, 0x3fc90fda
	v_fma_f32 v7, v5, s8, -v6
	v_fmac_f32_e32 v7, 0x33a22168, v5
	v_fmac_f32_e32 v7, 0x3fc90fda, v4
	v_lshrrev_b32_e32 v3, 30, v3
	v_add_f32_e32 v59, v6, v7
	v_add_u32_e32 v58, v14, v3
